# in-proj GEMM: workgroups that own one tile fewer start 8-16 us late so their epilogue store bursts do not coincide with the critical workgroups' bursts
# speedup vs baseline: 1.0225x; 1.0065x over previous
; __device__ __forceinline__ int opaque_tid() { int t = threadIdx.x; asm volatile("" : "+v"(t)); return t; }
; #define PG8_STAGE(bufoff, gbase, voff) do { _Pragma("unroll") for (int _i = 0; _i < 2; ++_i) \
;         __builtin_amdgcn_global_load_lds((const unsigned*)((const char*)(gbase) + (voff)[_i]), (LAS unsigned*)(lds + (bufoff) + ldsw + _i * 8192), 16, 0, 0); } while (0)
; #define PG8_BAR __builtin_amdgcn_s_barrier()
; template <class Epi, class Sched>
; __device__ __forceinline__ void gemm_phase(LAS unsigned char* lds, const Gemm g, const Sched& S, const Epi& E) {
;     const int tid = opaque_tid(), wid = __builtin_amdgcn_readfirstlane(tid >> 6), lane = tid & 63, wr = wid >> 2, wc = wid & 3, fr = lane & 15, fq = lane >> 4;
;     const int K = g.K, nt = K / BK;
;     unsigned voffA[2], voffB[2];
; #pragma unroll
;     for (int i = 0; i < 2; ++i) { int R, C; stage_rc(tid * 16 + i * 8192, R, C); const int Rb = Epi::PERM ? ((R & ~31) + perm32(R & 31)) : R;
;         voffA[i] = (unsigned)(R * K + C) * 2u; voffB[i] = (unsigned)(Rb * K + C) * 2u; }
;     ...
;     const char* cA = (const char*)g.A + (size_t)cur.pm * tstep; const char* cB = (const char*)g.Bt + (size_t)cur.pn * tstep;
;     S.a_ready(cur);
;     PG8_STAGE(PG8_SB(0, 0), cB, voffB); PG8_STAGE(PG8_SA(0, 0), cA, voffA); PG8_STAGE(PG8_SB(0, 1), cB + hstep, voffB); PG8_STAGE(PG8_SA(0, 1), cA + hstep, voffA);
;     if (wr == 1) PG8_BAR;
.LBB0_180:
	s_or_b64 exec, exec, s[0:1]
	v_readlane_b32 s0, v240, 24
	v_readlane_b32 s1, v240, 25
	s_mov_b32 s1, s3
	v_writelane_b32 v240, s0, 24
	s_waitcnt lgkmcnt(0)
	v_mov_b32_e32 v0, v135
	v_writelane_b32 v240, s1, 25
	v_readlane_b32 s0, v243, 39
	v_readlane_b32 s1, v243, 40
	s_barrier
	s_andn2_b64 vcc, exec, s[0:1]
	v_readfirstlane_b32 s5, v0
	s_cbranch_vccnz .LBB0_192
	v_lshlrev_b32_e32 v4, 4, v0
	v_add_u32_e32 v2, 0x2000, v4
	v_ashrrev_i32_e32 v1, 31, v2
	v_lshrrev_b32_e32 v1, 22, v1
	v_add_u32_e32 v1, v2, v1
	v_ashrrev_i32_e32 v1, 10, v1
	v_mul_i32_i24_e32 v3, 0x400, v1
	v_sub_u32_e32 v2, v2, v3
	v_lshrrev_b32_e32 v3, 4, v2
	v_bitop3_b32 v3, v3, v2, 32 bitop3:0x6c
	v_ashrrev_i32_e32 v2, 31, v3
	v_lshrrev_b32_e32 v2, 26, v2
	v_add_u32_e32 v5, v3, v2
	v_lshlrev_b32_e32 v6, 3, v1
	v_ashrrev_i32_e32 v2, 6, v5
	v_and_b32_e32 v6, -16, v6
	v_add_u32_e32 v6, v2, v6
	v_and_b32_e32 v7, 3, v2
	s_mov_b32 s2, 0x1fffe0
	v_lshrrev_b32_e32 v9, 2, v6
	v_lshlrev_b32_e32 v10, 1, v6
	v_and_b32_e32 v5, 0xc0, v5
	v_and_or_b32 v7, v6, s2, v7
	v_and_b32_e32 v9, 4, v9
	v_and_b32_e32 v10, 24, v10
	v_sub_u32_e32 v3, v3, v5
	v_or3_b32 v7, v7, v9, v10
	v_lshlrev_b32_e32 v9, 5, v1
	v_ashrrev_i16_sdwa v3, v176, sext(v3) dst_sel:DWORD dst_unused:UNUSED_PAD src0_sel:DWORD src1_sel:BYTE_0
	v_and_b32_e32 v9, 32, v9
	v_bfe_i32 v3, v3, 0, 16
	v_add_lshl_u32 v5, v9, v3, 1
	v_lshl_add_u32 v140, v7, 11, v5
	v_lshl_add_u32 v142, v6, 11, v5
	v_bfe_i32 v5, v0, 27, 1
	v_lshrrev_b32_e32 v5, 22, v5
	v_add_u32_e32 v5, v4, v5
	v_and_b32_e32 v5, 0xfffffc00, v5
	v_sub_u32_e32 v4, v4, v5
	v_lshrrev_b32_e32 v5, 4, v4
	v_bitop3_b32 v6, v5, v4, 32 bitop3:0x6c
	v_ashrrev_i32_e32 v5, 31, v0
	v_lshrrev_b32_e32 v5, 26, v5
	v_ashrrev_i32_e32 v4, 31, v4
	v_add_u32_e32 v5, v0, v5
	v_lshrrev_b32_e32 v4, 26, v4
	v_ashrrev_i32_e32 v5, 6, v5
	v_add_u32_e32 v4, v6, v4
	v_lshlrev_b32_e32 v7, 3, v5
	v_ashrrev_i32_e32 v4, 6, v4
	v_and_b32_e32 v7, -16, v7
	v_add_u32_e32 v7, v4, v7
	v_readlane_b32 s0, v240, 24
	v_and_b32_e32 v9, 3, v4
	v_lshrrev_b32_e32 v10, 2, v7
	v_lshlrev_b32_e32 v11, 1, v7
	s_mul_i32 s0, s0, 0x700000
	v_and_or_b32 v9, v7, s2, v9
	v_and_b32_e32 v10, 4, v10
	v_and_b32_e32 v11, 24, v11
	v_readlane_b32 s1, v240, 25
	s_add_u32 s6, s62, s0
	v_or3_b32 v9, v9, v10, v11
	v_mul_i32_i24_e32 v11, 64, v4
	s_addc_u32 s7, s63, 0
	s_ashr_i32 s1, s5, 6
	v_sub_u32_e32 v6, v6, v11
	s_ashr_i32 s0, s5, 8
	s_lshl_b32 s8, s1, 10
	v_lshlrev_b32_e32 v10, 5, v5
	v_ashrrev_i16_sdwa v6, v176, sext(v6) dst_sel:DWORD dst_unused:UNUSED_PAD src0_sel:DWORD src1_sel:BYTE_0
	v_readlane_b32 s10, v241, 18
	v_and_b32_e32 v10, 32, v10
	v_bfe_i32 v6, v6, 0, 16
	v_readlane_b32 s11, v241, 19
	s_add_u32 s66, s6, s10
	v_add_lshl_u32 v10, v10, v6, 1
	s_addc_u32 s67, s7, s11
	s_add_i32 s9, s8, 16
	v_lshl_add_u32 v144, v9, 11, v10
	s_cmp_lt_u32 s92, 0x70
	s_cbranch_scc1 .Lds184_x
	s_cmp_lg_u32 s46, 0x100
	s_cbranch_scc1 .Lds184_x
	s_sub_u32 s98, s92, 0x70
	s_lshr_b32 s98, s98, 4
	s_add_u32 s98, s98, 9
	s_min_u32 s98, s98, 20
.Lds184_l:
	s_sleep 32
	s_sub_u32 s98, s98, 1
	s_cmp_lg_u32 s98, 0
	s_cbranch_scc1 .Lds184_l
.Lds184_x:
	s_add_i32 m0, s9, 0x10000
	v_readlane_b32 s12, v241, 22
	global_load_lds_dwordx4 v144, s[66:67]
	s_add_i32 m0, s9, 0x12000
	v_lshl_add_u32 v146, v7, 11, v10
	global_load_lds_dwordx4 v140, s[66:67]
	s_mov_b32 m0, s9
	v_readlane_b32 s13, v241, 23
	s_add_i32 s10, s9, 0x2000
	v_readlane_b32 s14, v241, 24
	v_readlane_b32 s15, v241, 25
	s_movk_i32 s79, 0xef
	s_nop 0
	global_load_lds_dwordx4 v146, s[12:13]
	s_mov_b32 m0, s10
	s_nop 0
	global_load_lds_dwordx4 v142, s[12:13]
	s_add_u32 s12, s66, 0x40000
	s_addc_u32 s13, s67, 0
	s_add_i32 m0, s9, 0x14000
	s_add_i32 s11, s9, 0x4000
	global_load_lds_dwordx4 v144, s[12:13]
	s_add_i32 m0, s9, 0x16000
	s_nop 0
	global_load_lds_dwordx4 v140, s[12:13]
	s_mov_b32 m0, s11
	s_add_i32 s12, s9, 0x6000
	global_load_lds_dwordx4 v146, s[14:15]
	s_mov_b32 m0, s12
	s_cmp_lg_u32 s0, 1
	global_load_lds_dwordx4 v142, s[14:15]
	s_cbranch_scc1 .LBB0_183
	s_barrier
